# np13 + nt cache policy on the final LayerNorm output stores
# baseline (speedup 1.0000x reference)
.LBB0_1619:
	v_ashrrev_i32_e32 v5, 31, v4
	v_lshlrev_b64 v[0:1], 11, v[4:5]
	v_add_u32_e32 v36, 1, v4
	v_lshl_add_u64 v[20:21], v[6:7], 0, v[0:1]
	v_ashrrev_i32_e32 v37, 31, v36
	v_lshlrev_b64 v[20:21], 11, v[36:37]
	v_lshl_add_u64 v[28:29], v[6:7], 0, v[20:21]
	v_mov_b32_e32 v54, v132
	v_mov_b32_e32 v55, v133
	v_mov_b32_e32 v56, v134
	v_mov_b32_e32 v57, v135
	v_mov_b32_e32 v58, v128
	v_mov_b32_e32 v59, v129
	v_mov_b32_e32 v60, v130
	v_mov_b32_e32 v61, v131
	v_mov_b32_e32 v62, v116
	v_mov_b32_e32 v63, v117
	v_mov_b32_e32 v64, v118
	v_mov_b32_e32 v65, v119
	v_mov_b32_e32 v66, v112
	v_mov_b32_e32 v67, v113
	v_mov_b32_e32 v68, v114
	v_mov_b32_e32 v69, v115
	v_lshlrev_b64 v[36:37], 12, v[36:37]
	v_lshl_add_u64 v[36:37], v[12:13], 0, v[36:37]
	s_waitcnt vmcnt(16)
	v_mov_b32_e32 v0, v144
	v_mov_b32_e32 v1, v145
	v_mov_b32_e32 v2, v146
	v_mov_b32_e32 v3, v147
	v_mov_b32_e32 v16, v148
	v_mov_b32_e32 v17, v149
	v_mov_b32_e32 v18, v150
	v_mov_b32_e32 v19, v151
	v_mov_b32_e32 v20, v152
	v_mov_b32_e32 v21, v153
	v_mov_b32_e32 v22, v154
	v_mov_b32_e32 v23, v155
	v_mov_b32_e32 v24, v156
	v_mov_b32_e32 v25, v157
	v_mov_b32_e32 v26, v158
	v_mov_b32_e32 v27, v159
	v_lshlrev_b32_e32 v30, 16, v0
	v_and_b32_e32 v31, 0xffff0000, v0
	v_add_f32_e32 v40, 0, v30
	v_lshlrev_b32_e32 v70, 16, v20
	v_lshlrev_b32_e32 v0, 16, v1
	v_and_b32_e32 v71, 0xffff0000, v20
	v_add_f32_e32 v40, v40, v31
	v_add_f32_e32 v41, 0, v70
	v_and_b32_e32 v1, 0xffff0000, v1
	v_lshlrev_b32_e32 v20, 16, v21
	v_add_f32_e32 v40, v40, v0
	v_add_f32_e32 v41, v41, v71
	v_lshlrev_b32_e32 v28, 16, v2
	v_and_b32_e32 v21, 0xffff0000, v21
	v_add_f32_e32 v40, v40, v1
	v_add_f32_e32 v41, v41, v20
	v_and_b32_e32 v29, 0xffff0000, v2
	v_lshlrev_b32_e32 v38, 16, v22
	v_add_f32_e32 v40, v40, v28
	v_add_f32_e32 v41, v41, v21
	v_lshlrev_b32_e32 v2, 16, v3
	v_and_b32_e32 v39, 0xffff0000, v22
	v_add_f32_e32 v40, v40, v29
	v_add_f32_e32 v41, v41, v38
	v_and_b32_e32 v3, 0xffff0000, v3
	v_lshlrev_b32_e32 v22, 16, v23
	v_add_f32_e32 v40, v40, v2
	v_add_f32_e32 v41, v41, v39
	v_lshlrev_b32_e32 v34, 16, v16
	v_and_b32_e32 v23, 0xffff0000, v23
	v_add_f32_e32 v40, v40, v3
	v_add_f32_e32 v41, v41, v22
	v_and_b32_e32 v35, 0xffff0000, v16
	v_lshlrev_b32_e32 v74, 16, v24
	v_add_f32_e32 v40, v40, v34
	v_add_f32_e32 v41, v41, v23
	v_lshlrev_b32_e32 v16, 16, v17
	v_and_b32_e32 v75, 0xffff0000, v24
	v_add_f32_e32 v40, v40, v35
	v_add_f32_e32 v41, v41, v74
	v_and_b32_e32 v17, 0xffff0000, v17
	v_lshlrev_b32_e32 v24, 16, v25
	v_add_f32_e32 v40, v40, v16
	v_add_f32_e32 v41, v41, v75
	v_lshlrev_b32_e32 v32, 16, v18
	v_and_b32_e32 v25, 0xffff0000, v25
	v_add_f32_e32 v40, v40, v17
	v_add_f32_e32 v41, v41, v24
	v_and_b32_e32 v33, 0xffff0000, v18
	v_lshlrev_b32_e32 v72, 16, v26
	v_add_f32_e32 v40, v40, v32
	v_add_f32_e32 v41, v41, v25
	v_lshlrev_b32_e32 v18, 16, v19
	v_and_b32_e32 v73, 0xffff0000, v26
	v_add_f32_e32 v40, v40, v33
	v_add_f32_e32 v41, v41, v72
	v_and_b32_e32 v19, 0xffff0000, v19
	v_lshlrev_b32_e32 v26, 16, v27
	v_add_f32_e32 v40, v40, v18
	v_add_f32_e32 v41, v41, v73
	v_and_b32_e32 v27, 0xffff0000, v27
	v_add_f32_e32 v40, v40, v19
	v_add_f32_e32 v41, v41, v26
	ds_bpermute_b32 v42, v48, v40
	v_add_f32_e32 v41, v41, v27
	ds_bpermute_b32 v43, v48, v41
	s_waitcnt lgkmcnt(1)
	v_add_f32_e32 v40, v40, v42
	ds_bpermute_b32 v42, v49, v40
	s_waitcnt lgkmcnt(1)
	v_add_f32_e32 v41, v41, v43
	ds_bpermute_b32 v43, v49, v41
	s_waitcnt lgkmcnt(1)
	v_add_f32_e32 v40, v40, v42
	ds_bpermute_b32 v42, v50, v40
	s_waitcnt lgkmcnt(1)
	v_add_f32_e32 v41, v41, v43
	ds_bpermute_b32 v43, v50, v41
	s_waitcnt lgkmcnt(1)
	v_add_f32_e32 v40, v40, v42
	ds_bpermute_b32 v42, v51, v40
	s_waitcnt lgkmcnt(1)
	v_add_f32_e32 v41, v41, v43
	ds_bpermute_b32 v43, v51, v41
	s_waitcnt lgkmcnt(1)
	v_add_f32_e32 v40, v40, v42
	ds_bpermute_b32 v42, v52, v40
	s_waitcnt lgkmcnt(1)
	v_add_f32_e32 v41, v41, v43
	ds_bpermute_b32 v43, v52, v41
	s_waitcnt lgkmcnt(1)
	v_add_f32_e32 v40, v40, v42
	ds_bpermute_b32 v42, v53, v40
	s_waitcnt lgkmcnt(1)
	v_add_f32_e32 v41, v41, v43
	ds_bpermute_b32 v43, v53, v41
	s_waitcnt lgkmcnt(1)
	v_add_f32_e32 v40, v40, v42
	v_mul_f32_e32 v46, 0x3a800000, v40
	s_waitcnt lgkmcnt(0)
	v_add_f32_e32 v76, v41, v43
	v_pk_add_f32 v[84:85], v[0:1], v[46:47] op_sel_hi:[1,0] neg_lo:[0,1] neg_hi:[0,1]
	v_mul_f32_e32 v0, 0x3a800000, v76
	v_pk_add_f32 v[82:83], v[30:31], v[46:47] op_sel_hi:[1,0] neg_lo:[0,1] neg_hi:[0,1]
	v_pk_add_f32 v[86:87], v[28:29], v[46:47] op_sel_hi:[1,0] neg_lo:[0,1] neg_hi:[0,1]
	v_pk_add_f32 v[28:29], v[70:71], v[0:1] op_sel_hi:[1,0] neg_lo:[0,1] neg_hi:[0,1]
	v_mov_b32_e32 v77, v83
	v_mov_b32_e32 v76, v29
	v_mov_b32_e32 v71, v82
	v_pk_add_f32 v[30:31], v[20:21], v[0:1] op_sel_hi:[1,0] neg_lo:[0,1] neg_hi:[0,1]
	v_mov_b32_e32 v70, v28
	v_pk_mul_f32 v[76:77], v[76:77], v[76:77]
	v_mov_b32_e32 v79, v84
	v_mov_b32_e32 v78, v30
	v_pk_fma_f32 v[70:71], v[70:71], v[70:71], v[76:77]
	v_pk_add_f32 v[40:41], v[34:35], v[46:47] op_sel_hi:[1,0] neg_lo:[0,1] neg_hi:[0,1]
	v_pk_add_f32 v[42:43], v[32:33], v[46:47] op_sel_hi:[1,0] neg_lo:[0,1] neg_hi:[0,1]
	v_pk_add_f32 v[32:33], v[38:39], v[0:1] op_sel_hi:[1,0] neg_lo:[0,1] neg_hi:[0,1]
	v_pk_add_f32 v[34:35], v[22:23], v[0:1] op_sel_hi:[1,0] neg_lo:[0,1] neg_hi:[0,1]
	v_pk_add_f32 v[22:23], v[24:25], v[0:1] op_sel_hi:[1,0] neg_lo:[0,1] neg_hi:[0,1]
	v_mov_b32_e32 v25, v85
	v_mov_b32_e32 v24, v31
	v_pk_fma_f32 v[70:71], v[78:79], v[78:79], v[70:71]
	v_mov_b32_e32 v39, v86
	v_mov_b32_e32 v38, v32
	v_pk_fma_f32 v[24:25], v[24:25], v[24:25], v[70:71]
	v_pk_add_f32 v[88:89], v[2:3], v[46:47] op_sel_hi:[1,0] neg_lo:[0,1] neg_hi:[0,1]
	v_pk_add_f32 v[20:21], v[72:73], v[0:1] op_sel_hi:[1,0] neg_lo:[0,1] neg_hi:[0,1]
	v_mov_b32_e32 v73, v87
	v_mov_b32_e32 v72, v33
	v_pk_fma_f32 v[24:25], v[38:39], v[38:39], v[24:25]
	v_pk_add_f32 v[44:45], v[16:17], v[46:47] op_sel_hi:[1,0] neg_lo:[0,1] neg_hi:[0,1]
	v_pk_add_f32 v[46:47], v[18:19], v[46:47] op_sel_hi:[1,0] neg_lo:[0,1] neg_hi:[0,1]
	v_pk_add_f32 v[18:19], v[74:75], v[0:1] op_sel_hi:[1,0] neg_lo:[0,1] neg_hi:[0,1]
	v_mov_b32_e32 v75, v88
	v_mov_b32_e32 v74, v34
	v_pk_fma_f32 v[24:25], v[72:73], v[72:73], v[24:25]
	v_mov_b32_e32 v81, v89
	v_mov_b32_e32 v80, v35
	v_pk_fma_f32 v[24:25], v[74:75], v[74:75], v[24:25]
	v_mov_b32_e32 v92, v18
	v_pk_fma_f32 v[24:25], v[80:81], v[80:81], v[24:25]
	v_mov_b32_e32 v93, v40
	v_pk_fma_f32 v[24:25], v[92:93], v[92:93], v[24:25]
	v_mov_b32_e32 v38, v19
	v_mov_b32_e32 v39, v41
	v_pk_fma_f32 v[24:25], v[38:39], v[38:39], v[24:25]
	v_mov_b32_e32 v38, v22
	v_mov_b32_e32 v39, v44
	v_pk_mul_f32 v[2:3], v[42:43], v[42:43]
	v_pk_mul_f32 v[90:91], v[20:21], v[20:21]
	v_pk_fma_f32 v[24:25], v[38:39], v[38:39], v[24:25]
	v_mov_b32_e32 v38, v23
	v_mov_b32_e32 v39, v45
	v_pk_fma_f32 v[24:25], v[38:39], v[38:39], v[24:25]
	v_mov_b32_e32 v38, v90
	v_mov_b32_e32 v39, v2
	v_pk_add_f32 v[26:27], v[26:27], v[0:1] op_sel_hi:[1,0] neg_lo:[0,1] neg_hi:[0,1]
	v_pk_mul_f32 v[16:17], v[46:47], v[46:47]
	v_pk_add_f32 v[24:25], v[38:39], v[24:25]
	v_pk_mul_f32 v[0:1], v[26:27], v[26:27]
	v_mov_b32_e32 v2, v91
	v_pk_add_f32 v[2:3], v[2:3], v[24:25]
	v_mov_b32_e32 v24, v0
	v_mov_b32_e32 v25, v16
	v_pk_add_f32 v[2:3], v[24:25], v[2:3]
	v_mov_b32_e32 v16, v1
	v_pk_add_f32 v[0:1], v[16:17], v[2:3]
	ds_bpermute_b32 v3, v48, v1
	ds_bpermute_b32 v2, v48, v0
	v_add_u32_e32 v24, 2, v4
	v_ashrrev_i32_e32 v25, 31, v24
	v_lshlrev_b64 v[16:17], 11, v[24:25]
	v_lshl_add_u64 v[16:17], v[6:7], 0, v[16:17]
	s_waitcnt lgkmcnt(0)
	v_pk_add_f32 v[0:1], v[0:1], v[2:3]
	ds_bpermute_b32 v3, v49, v1
	ds_bpermute_b32 v2, v49, v0
	v_mov_b32_e32 v70, v160
	v_mov_b32_e32 v71, v161
	v_mov_b32_e32 v72, v162
	v_mov_b32_e32 v73, v163
	v_mov_b32_e32 v74, v164
	v_mov_b32_e32 v75, v165
	v_mov_b32_e32 v76, v166
	v_mov_b32_e32 v77, v167
	v_add_u32_e32 v16, 3, v4
	v_ashrrev_i32_e32 v17, 31, v16
	v_lshlrev_b64 v[38:39], 11, v[16:17]
	s_waitcnt lgkmcnt(0)
	v_pk_add_f32 v[0:1], v[0:1], v[2:3]
	ds_bpermute_b32 v3, v50, v1
	ds_bpermute_b32 v2, v50, v0
	v_lshl_add_u64 v[90:91], v[6:7], 0, v[38:39]
	v_lshlrev_b64 v[16:17], 12, v[16:17]
	s_waitcnt lgkmcnt(0)
	v_pk_add_f32 v[0:1], v[0:1], v[2:3]
	ds_bpermute_b32 v3, v51, v1
	ds_bpermute_b32 v2, v51, v0
	s_waitcnt lgkmcnt(0)
	v_pk_add_f32 v[0:1], v[0:1], v[2:3]
	ds_bpermute_b32 v3, v52, v1
	ds_bpermute_b32 v2, v52, v0
	s_waitcnt lgkmcnt(0)
	v_pk_add_f32 v[0:1], v[0:1], v[2:3]
	ds_bpermute_b32 v3, v53, v1
	ds_bpermute_b32 v2, v53, v0
	s_waitcnt lgkmcnt(0)
	v_pk_add_f32 v[0:1], v[0:1], v[2:3]
	s_nop 0
	v_pk_fma_f32 v[38:39], v[0:1], s[2:3], v[14:15] op_sel_hi:[1,0,0]
	s_nop 0
	v_mul_f32_e32 v0, 0x4b800000, v39
	v_cmp_gt_f32_e32 vcc, s4, v39
	s_nop 1
	v_cndmask_b32_e32 v0, v39, v0, vcc
	v_rsq_f32_e32 v39, v0
	v_mov_b32_e32 v78, v168
	v_mov_b32_e32 v79, v169
	v_mov_b32_e32 v80, v170
	v_mov_b32_e32 v81, v171
	v_mov_b32_e32 v0, v172
	v_mov_b32_e32 v1, v173
	v_mov_b32_e32 v2, v174
	v_mov_b32_e32 v3, v175
	v_add_u32_e32 v192, s3, v4
	v_cmp_ge_i32_e64 s[8:9], s5, v192
	s_and_saveexec_b64 s[12:13], s[8:9]
	v_ashrrev_i32_e32 v193, 31, v192
	v_lshlrev_b64 v[194:195], 11, v[192:193]
	v_lshl_add_u64 v[194:195], v[6:7], 0, v[194:195]
	v_lshl_add_u64 v[196:197], v[194:195], 0, s[14:15]
	global_load_dwordx4 v[144:147], v[194:195], off
	global_load_dwordx4 v[148:151], v[194:195], off offset:1024
	global_load_dwordx4 v[152:155], v[194:195], off offset:2048
	global_load_dwordx4 v[156:159], v[194:195], off offset:3072
	global_load_dwordx4 v[160:163], v[196:197], off
	global_load_dwordx4 v[164:167], v[196:197], off offset:1024
	global_load_dwordx4 v[168:171], v[196:197], off offset:2048
	global_load_dwordx4 v[172:175], v[196:197], off offset:3072
	s_mov_b64 exec, s[12:13]
	v_lshlrev_b64 v[90:91], 12, v[4:5]
	v_lshl_add_u64 v[90:91], v[12:13], 0, v[90:91]
	v_mul_f32_e32 v5, 0x45800000, v39
	v_cndmask_b32_e32 v92, v39, v5, vcc
	v_pk_mul_f32 v[82:83], v[82:83], v[92:93] op_sel_hi:[1,0]
	v_pk_mul_f32 v[84:85], v[84:85], v[92:93] op_sel_hi:[1,0]
	v_pk_fma_f32 v[58:59], v[58:59], v[82:83], v[66:67]
	v_pk_fma_f32 v[60:61], v[60:61], v[84:85], v[68:69]
	v_pk_mul_f32 v[66:67], v[86:87], v[92:93] op_sel_hi:[1,0]
	v_pk_mul_f32 v[68:69], v[88:89], v[92:93] op_sel_hi:[1,0]
	v_pk_fma_f32 v[54:55], v[54:55], v[66:67], v[62:63]
	v_pk_fma_f32 v[56:57], v[56:57], v[68:69], v[64:65]
	global_store_dwordx4 v[90:91], v[58:61], off nt
	global_store_dwordx4 v[90:91], v[54:57], off offset:16 nt
	s_nop 1
	v_mov_b32_e32 v54, v120
	v_mov_b32_e32 v55, v121
	v_mov_b32_e32 v56, v122
	v_mov_b32_e32 v57, v123
	s_nop 0
	v_mov_b32_e32 v58, v136
	v_mov_b32_e32 v59, v137
	v_mov_b32_e32 v60, v138
	v_mov_b32_e32 v61, v139
	v_mov_b32_e32 v62, v140
	v_mov_b32_e32 v63, v141
	v_mov_b32_e32 v64, v142
	v_mov_b32_e32 v65, v143
	v_mov_b32_e32 v66, v124
	v_mov_b32_e32 v67, v125
	v_mov_b32_e32 v68, v126
	v_mov_b32_e32 v69, v127
	v_pk_mul_f32 v[44:45], v[44:45], v[92:93] op_sel_hi:[1,0]
	v_pk_mul_f32 v[40:41], v[40:41], v[92:93] op_sel_hi:[1,0]
	v_pk_mul_f32 v[46:47], v[46:47], v[92:93] op_sel_hi:[1,0]
	v_pk_mul_f32 v[84:85], v[42:43], v[92:93] op_sel_hi:[1,0]
	v_cmp_gt_f32_e32 vcc, s4, v38
	v_add_u32_e32 v4, s3, v4
	v_lshlrev_b32_e32 v82, 16, v72
	v_and_b32_e32 v83, 0xffff0000, v72
	v_lshlrev_b32_e32 v72, 16, v74
	v_lshlrev_b32_e32 v92, 16, v1
	v_and_b32_e32 v93, 0xffff0000, v1
	v_lshlrev_b32_e32 v86, 16, v2
	v_and_b32_e32 v87, 0xffff0000, v2
	v_lshlrev_b32_e32 v88, 16, v3
	v_and_b32_e32 v89, 0xffff0000, v3
	v_pk_fma_f32 v[40:41], v[58:59], v[40:41], v[54:55]
	v_pk_fma_f32 v[42:43], v[60:61], v[44:45], v[56:57]
	v_pk_fma_f32 v[44:45], v[62:63], v[84:85], v[66:67]
	v_pk_fma_f32 v[46:47], v[64:65], v[46:47], v[68:69]
	global_store_dwordx4 v[90:91], v[40:43], off offset:2048 nt
	global_store_dwordx4 v[90:91], v[44:47], off offset:2064 nt
	s_nop 0
	v_mov_b32_e32 v40, v132
	v_mov_b32_e32 v41, v133
	v_mov_b32_e32 v42, v134
	v_mov_b32_e32 v43, v135
	s_nop 0
	v_mov_b32_e32 v44, v128
	v_mov_b32_e32 v45, v129
	v_mov_b32_e32 v46, v130
	v_mov_b32_e32 v47, v131
	v_mov_b32_e32 v54, v116
	v_mov_b32_e32 v55, v117
	v_mov_b32_e32 v56, v118
	v_mov_b32_e32 v57, v119
	v_mov_b32_e32 v58, v112
	v_mov_b32_e32 v59, v113
	v_mov_b32_e32 v60, v114
	v_mov_b32_e32 v61, v115
	v_lshlrev_b32_e32 v64, 16, v70
	v_and_b32_e32 v65, 0xffff0000, v70
	v_lshlrev_b32_e32 v90, 16, v0
	v_and_b32_e32 v91, 0xffff0000, v0
	v_add_f32_e32 v0, 0, v64
	v_lshlrev_b32_e32 v66, 16, v71
	v_add_f32_e32 v0, v0, v65
	v_and_b32_e32 v67, 0xffff0000, v71
	v_add_f32_e32 v0, v0, v66
	v_add_f32_e32 v0, v0, v67
	v_add_f32_e32 v0, v0, v82
	v_lshlrev_b32_e32 v62, 16, v73
	v_lshlrev_b32_e32 v84, 16, v78
	v_add_f32_e32 v0, v0, v83
	v_and_b32_e32 v63, 0xffff0000, v73
	v_and_b32_e32 v85, 0xffff0000, v78
	v_add_f32_e32 v1, 0, v84
	v_add_f32_e32 v0, v0, v62
	v_lshlrev_b32_e32 v78, 16, v79
	v_add_f32_e32 v1, v1, v85
	v_add_f32_e32 v0, v0, v63
	v_and_b32_e32 v73, 0xffff0000, v74
	v_and_b32_e32 v79, 0xffff0000, v79
	v_add_f32_e32 v1, v1, v78
	v_add_f32_e32 v0, v0, v72
	v_lshlrev_b32_e32 v68, 16, v76
	v_and_b32_e32 v69, 0xffff0000, v76
	v_lshlrev_b32_e32 v74, 16, v75
	v_lshlrev_b32_e32 v76, 16, v80
	v_add_f32_e32 v1, v1, v79
	v_add_f32_e32 v0, v0, v73
	v_lshlrev_b32_e32 v70, 16, v77
	v_and_b32_e32 v71, 0xffff0000, v77
	v_and_b32_e32 v75, 0xffff0000, v75
	v_and_b32_e32 v77, 0xffff0000, v80
	v_add_f32_e32 v1, v1, v76
	v_add_f32_e32 v0, v0, v74
	v_lshlrev_b32_e32 v80, 16, v81
	v_add_f32_e32 v1, v1, v77
	v_add_f32_e32 v0, v0, v75
	v_and_b32_e32 v81, 0xffff0000, v81
	v_add_f32_e32 v1, v1, v80
	v_add_f32_e32 v0, v0, v68
	v_add_f32_e32 v1, v1, v81
	v_add_f32_e32 v0, v0, v69
	v_add_f32_e32 v1, v1, v90
	v_add_f32_e32 v0, v0, v70
	v_add_f32_e32 v1, v1, v91
	v_add_f32_e32 v0, v0, v71
	v_add_f32_e32 v1, v1, v92
	ds_bpermute_b32 v2, v48, v0
	v_add_f32_e32 v1, v1, v93
	v_add_f32_e32 v1, v1, v86
	v_add_f32_e32 v1, v1, v87
	v_add_f32_e32 v1, v1, v88
	v_add_f32_e32 v1, v1, v89
	s_waitcnt lgkmcnt(0)
	v_add_f32_e32 v5, v0, v2
	v_mul_f32_e32 v0, 0x4b800000, v38
	ds_bpermute_b32 v3, v48, v1
	v_cndmask_b32_e32 v0, v38, v0, vcc
	v_rsq_f32_e32 v0, v0
	ds_bpermute_b32 v96, v49, v5
	s_waitcnt lgkmcnt(1)
	v_add_f32_e32 v95, v1, v3
	v_mul_f32_e32 v1, 0x45800000, v0
	v_cndmask_b32_e32 v94, v0, v1, vcc
	v_pk_mul_f32 v[2:3], v[30:31], v[94:95] op_sel_hi:[1,0]
	v_pk_mul_f32 v[0:1], v[28:29], v[94:95] op_sel_hi:[1,0]
	v_pk_mul_f32 v[30:31], v[34:35], v[94:95] op_sel_hi:[1,0]
	v_pk_mul_f32 v[28:29], v[32:33], v[94:95] op_sel_hi:[1,0]
	ds_bpermute_b32 v97, v49, v95
	v_pk_mul_f32 v[22:23], v[22:23], v[94:95] op_sel_hi:[1,0]
	v_pk_mul_f32 v[18:19], v[18:19], v[94:95] op_sel_hi:[1,0]
	v_pk_mul_f32 v[26:27], v[26:27], v[94:95] op_sel_hi:[1,0]
	v_pk_fma_f32 v[28:29], v[40:41], v[28:29], v[54:55]
	v_pk_fma_f32 v[0:1], v[44:45], v[0:1], v[58:59]
	v_pk_fma_f32 v[2:3], v[46:47], v[2:3], v[60:61]
	v_pk_fma_f32 v[30:31], v[42:43], v[30:31], v[56:57]
	global_store_dwordx4 v[36:37], v[0:3], off nt
	global_store_dwordx4 v[36:37], v[28:31], off offset:16 nt
	v_mov_b32_e32 v32, v140
	v_mov_b32_e32 v33, v141
	v_mov_b32_e32 v34, v142
	v_mov_b32_e32 v35, v143
	v_mov_b32_e32 v38, v136
	v_mov_b32_e32 v39, v137
	v_mov_b32_e32 v40, v138
	v_mov_b32_e32 v41, v139
	v_mov_b32_e32 v42, v124
	v_mov_b32_e32 v43, v125
	v_mov_b32_e32 v44, v126
	v_mov_b32_e32 v45, v127
	v_mov_b32_e32 v54, v120
	v_mov_b32_e32 v55, v121
	v_mov_b32_e32 v56, v122
	v_mov_b32_e32 v57, v123
	s_waitcnt lgkmcnt(1)
	v_add_f32_e32 v0, v5, v96
	s_waitcnt lgkmcnt(0)
	v_add_f32_e32 v1, v95, v97
	ds_bpermute_b32 v2, v50, v0
	ds_bpermute_b32 v3, v50, v1
	v_pk_mul_f32 v[94:95], v[20:21], v[94:95] op_sel_hi:[1,0]
	s_waitcnt lgkmcnt(1)
	v_add_f32_e32 v0, v0, v2
	s_waitcnt lgkmcnt(0)
	v_add_f32_e32 v1, v1, v3
	ds_bpermute_b32 v2, v51, v0
	ds_bpermute_b32 v3, v51, v1
	s_waitcnt lgkmcnt(1)
	v_add_f32_e32 v0, v0, v2
	s_waitcnt lgkmcnt(0)
	v_add_f32_e32 v1, v1, v3
	ds_bpermute_b32 v2, v52, v0
	ds_bpermute_b32 v3, v52, v1
	s_waitcnt lgkmcnt(1)
	v_add_f32_e32 v0, v0, v2
	s_waitcnt lgkmcnt(0)
	v_add_f32_e32 v1, v1, v3
	ds_bpermute_b32 v2, v53, v0
	ds_bpermute_b32 v3, v53, v1
	s_waitcnt lgkmcnt(1)
	v_add_f32_e32 v0, v0, v2
	s_waitcnt lgkmcnt(0)
	v_add_f32_e32 v1, v1, v3
	v_mul_f32_e32 v0, 0x3a800000, v0
	v_mul_f32_e32 v30, 0x3a800000, v1
	v_pk_add_f32 v[46:47], v[64:65], v[0:1] op_sel_hi:[1,0] neg_lo:[0,1] neg_hi:[0,1]
	v_pk_add_f32 v[64:65], v[72:73], v[0:1] op_sel_hi:[1,0] neg_lo:[0,1] neg_hi:[0,1]
	v_pk_add_f32 v[72:73], v[84:85], v[30:31] op_sel_hi:[1,0] neg_lo:[0,1] neg_hi:[0,1]
	v_pk_add_f32 v[58:59], v[66:67], v[0:1] op_sel_hi:[1,0] neg_lo:[0,1] neg_hi:[0,1]
	v_pk_add_f32 v[60:61], v[82:83], v[0:1] op_sel_hi:[1,0] neg_lo:[0,1] neg_hi:[0,1]
	v_pk_add_f32 v[62:63], v[62:63], v[0:1] op_sel_hi:[1,0] neg_lo:[0,1] neg_hi:[0,1]
	v_pk_add_f32 v[66:67], v[74:75], v[0:1] op_sel_hi:[1,0] neg_lo:[0,1] neg_hi:[0,1]
	v_pk_add_f32 v[68:69], v[68:69], v[0:1] op_sel_hi:[1,0] neg_lo:[0,1] neg_hi:[0,1]
	v_pk_add_f32 v[70:71], v[70:71], v[0:1] op_sel_hi:[1,0] neg_lo:[0,1] neg_hi:[0,1]
	v_pk_add_f32 v[74:75], v[78:79], v[30:31] op_sel_hi:[1,0] neg_lo:[0,1] neg_hi:[0,1]
	v_pk_add_f32 v[76:77], v[76:77], v[30:31] op_sel_hi:[1,0] neg_lo:[0,1] neg_hi:[0,1]
	v_pk_add_f32 v[78:79], v[80:81], v[30:31] op_sel_hi:[1,0] neg_lo:[0,1] neg_hi:[0,1]
	v_pk_add_f32 v[0:1], v[90:91], v[30:31] op_sel_hi:[1,0] neg_lo:[0,1] neg_hi:[0,1]
	v_pk_add_f32 v[28:29], v[92:93], v[30:31] op_sel_hi:[1,0] neg_lo:[0,1] neg_hi:[0,1]
	v_pk_add_f32 v[2:3], v[86:87], v[30:31] op_sel_hi:[1,0] neg_lo:[0,1] neg_hi:[0,1]
	v_pk_add_f32 v[30:31], v[88:89], v[30:31] op_sel_hi:[1,0] neg_lo:[0,1] neg_hi:[0,1]
	v_mov_b32_e32 v86, v73
	v_mov_b32_e32 v87, v47
	v_pk_mul_f32 v[82:83], v[70:71], v[70:71]
	v_mov_b32_e32 v84, v72
	v_mov_b32_e32 v85, v46
	v_mov_b32_e32 v88, v74
	v_mov_b32_e32 v89, v58
	v_mov_b32_e32 v92, v75
	v_mov_b32_e32 v93, v59
	v_mov_b32_e32 v96, v76
	v_mov_b32_e32 v97, v60
	v_mov_b32_e32 v98, v77
	v_mov_b32_e32 v99, v61
	v_mov_b32_e32 v100, v78
	v_mov_b32_e32 v101, v62
	v_mov_b32_e32 v102, v79
	v_mov_b32_e32 v103, v63
	v_mov_b32_e32 v104, v0
	v_mov_b32_e32 v105, v64
	v_mov_b32_e32 v106, v1
	v_mov_b32_e32 v107, v65
	v_mov_b32_e32 v108, v28
	v_mov_b32_e32 v109, v66
	v_pk_mul_f32 v[80:81], v[68:69], v[68:69]
	v_pk_mul_f32 v[90:91], v[2:3], v[2:3]
	v_mov_b32_e32 v110, v29
	v_mov_b32_e32 v111, v67
	v_pk_fma_f32 v[32:33], v[32:33], v[94:95], v[42:43]
	v_pk_fma_f32 v[18:19], v[38:39], v[18:19], v[54:55]
	v_pk_fma_f32 v[20:21], v[40:41], v[22:23], v[56:57]
	v_pk_fma_f32 v[34:35], v[34:35], v[26:27], v[44:45]
	global_store_dwordx4 v[36:37], v[18:21], off offset:2048 nt
	global_store_dwordx4 v[36:37], v[32:35], off offset:2064 nt
	s_nop 0
	v_mov_b32_e32 v18, v132
	v_mov_b32_e32 v19, v133
	v_mov_b32_e32 v20, v134
	v_mov_b32_e32 v21, v135
	s_nop 0
	v_mov_b32_e32 v32, v128
	v_mov_b32_e32 v33, v129
	v_mov_b32_e32 v34, v130
	v_mov_b32_e32 v35, v131
	v_mov_b32_e32 v36, v116
	v_mov_b32_e32 v37, v117
	v_mov_b32_e32 v38, v118
	v_mov_b32_e32 v39, v119
	v_mov_b32_e32 v40, v112
	v_mov_b32_e32 v41, v113
	v_mov_b32_e32 v42, v114
	v_mov_b32_e32 v43, v115
	v_pk_mul_f32 v[22:23], v[30:31], v[30:31]
	v_pk_mul_f32 v[26:27], v[86:87], v[86:87]
	v_mov_b32_e32 v54, v22
	v_mov_b32_e32 v55, v82
	v_mov_b32_e32 v82, v23
	v_pk_fma_f32 v[22:23], v[84:85], v[84:85], v[26:27]
	v_mov_b32_e32 v44, v90
	v_pk_fma_f32 v[22:23], v[88:89], v[88:89], v[22:23]
	v_mov_b32_e32 v45, v80
	v_pk_fma_f32 v[22:23], v[92:93], v[92:93], v[22:23]
	v_mov_b32_e32 v80, v91
	v_pk_fma_f32 v[22:23], v[96:97], v[96:97], v[22:23]
	s_nop 0
	v_pk_fma_f32 v[22:23], v[98:99], v[98:99], v[22:23]
	s_nop 0
	v_pk_fma_f32 v[22:23], v[100:101], v[100:101], v[22:23]
	s_nop 0
	v_pk_fma_f32 v[22:23], v[102:103], v[102:103], v[22:23]
	s_nop 0
	v_pk_fma_f32 v[22:23], v[104:105], v[104:105], v[22:23]
	s_nop 0
	v_pk_fma_f32 v[22:23], v[106:107], v[106:107], v[22:23]
	s_nop 0
	v_pk_fma_f32 v[22:23], v[108:109], v[108:109], v[22:23]
	s_nop 0
	v_pk_fma_f32 v[22:23], v[110:111], v[110:111], v[22:23]
	s_nop 0
	v_pk_add_f32 v[22:23], v[44:45], v[22:23]
	s_nop 0
	v_pk_add_f32 v[22:23], v[80:81], v[22:23]
	s_nop 0
	v_pk_add_f32 v[22:23], v[54:55], v[22:23]
	s_nop 0
	v_pk_add_f32 v[22:23], v[82:83], v[22:23]
	ds_bpermute_b32 v27, v48, v23
	ds_bpermute_b32 v26, v48, v22
	s_waitcnt lgkmcnt(0)
	v_pk_add_f32 v[22:23], v[22:23], v[26:27]
	ds_bpermute_b32 v27, v49, v23
	ds_bpermute_b32 v26, v49, v22
	s_waitcnt lgkmcnt(0)
	v_pk_add_f32 v[22:23], v[22:23], v[26:27]
	ds_bpermute_b32 v27, v50, v23
	ds_bpermute_b32 v26, v50, v22
	s_waitcnt lgkmcnt(0)
	v_pk_add_f32 v[22:23], v[22:23], v[26:27]
	ds_bpermute_b32 v27, v51, v23
	ds_bpermute_b32 v26, v51, v22
	s_waitcnt lgkmcnt(0)
	v_pk_add_f32 v[22:23], v[22:23], v[26:27]
	ds_bpermute_b32 v27, v52, v23
	ds_bpermute_b32 v26, v52, v22
	s_waitcnt lgkmcnt(0)
	v_pk_add_f32 v[22:23], v[22:23], v[26:27]
	ds_bpermute_b32 v27, v53, v23
	ds_bpermute_b32 v26, v53, v22
	s_waitcnt lgkmcnt(0)
	v_pk_add_f32 v[22:23], v[22:23], v[26:27]
	s_nop 0
	v_pk_fma_f32 v[26:27], v[22:23], s[2:3], v[14:15] op_sel_hi:[1,0,0]
	v_lshlrev_b64 v[22:23], 12, v[24:25]
	v_mul_f32_e32 v5, 0x4b800000, v27
	v_cmp_gt_f32_e32 vcc, s4, v27
	v_lshl_add_u64 v[44:45], v[12:13], 0, v[22:23]
	s_nop 0
	v_cndmask_b32_e32 v5, v27, v5, vcc
	v_rsq_f32_e32 v5, v5
	s_nop 0
	v_mul_f32_e32 v22, 0x45800000, v5
	v_cndmask_b32_e32 v54, v5, v22, vcc
	v_pk_mul_f32 v[24:25], v[58:59], v[54:55] op_sel_hi:[1,0]
	v_pk_mul_f32 v[22:23], v[46:47], v[54:55] op_sel_hi:[1,0]
	v_pk_mul_f32 v[46:47], v[62:63], v[54:55] op_sel_hi:[1,0]
	v_pk_mul_f32 v[56:57], v[60:61], v[54:55] op_sel_hi:[1,0]
	v_pk_fma_f32 v[22:23], v[32:33], v[22:23], v[40:41]
	v_pk_fma_f32 v[24:25], v[34:35], v[24:25], v[42:43]
	v_pk_fma_f32 v[18:19], v[18:19], v[56:57], v[36:37]
	v_pk_fma_f32 v[20:21], v[20:21], v[46:47], v[38:39]
	global_store_dwordx4 v[44:45], v[22:25], off nt
	global_store_dwordx4 v[44:45], v[18:21], off offset:16 nt
	s_nop 1
	v_mov_b32_e32 v18, v120
	v_mov_b32_e32 v19, v121
	v_mov_b32_e32 v20, v122
	v_mov_b32_e32 v21, v123
	s_nop 0
	v_mov_b32_e32 v22, v136
	v_mov_b32_e32 v23, v137
	v_mov_b32_e32 v24, v138
	v_mov_b32_e32 v25, v139
	v_mov_b32_e32 v32, v140
	v_mov_b32_e32 v33, v141
	v_mov_b32_e32 v34, v142
	v_mov_b32_e32 v35, v143
	v_mov_b32_e32 v36, v124
	v_mov_b32_e32 v37, v125
	v_mov_b32_e32 v38, v126
	v_mov_b32_e32 v39, v127
	v_pk_mul_f32 v[40:41], v[66:67], v[54:55] op_sel_hi:[1,0]
	v_pk_mul_f32 v[42:43], v[64:65], v[54:55] op_sel_hi:[1,0]
	v_pk_mul_f32 v[46:47], v[70:71], v[54:55] op_sel_hi:[1,0]
	v_pk_mul_f32 v[54:55], v[68:69], v[54:55] op_sel_hi:[1,0]
	v_mul_f32_e32 v5, 0x4b800000, v26
	v_cmp_gt_f32_e32 vcc, s4, v26
	v_pk_fma_f32 v[18:19], v[22:23], v[42:43], v[18:19]
	v_pk_fma_f32 v[20:21], v[24:25], v[40:41], v[20:21]
	v_pk_fma_f32 v[22:23], v[32:33], v[54:55], v[36:37]
	v_pk_fma_f32 v[24:25], v[34:35], v[46:47], v[38:39]
	global_store_dwordx4 v[44:45], v[18:21], off offset:2048 nt
	global_store_dwordx4 v[44:45], v[22:25], off offset:2064 nt
	s_nop 0
	v_mov_b32_e32 v18, v112
	v_mov_b32_e32 v19, v113
	v_mov_b32_e32 v20, v114
	v_mov_b32_e32 v21, v115
	s_nop 0
	v_mov_b32_e32 v22, v128
	v_mov_b32_e32 v23, v129
	v_mov_b32_e32 v24, v130
	v_mov_b32_e32 v25, v131
	v_mov_b32_e32 v32, v132
	v_mov_b32_e32 v33, v133
	v_mov_b32_e32 v34, v134
	v_mov_b32_e32 v35, v135
	v_mov_b32_e32 v36, v116
	v_mov_b32_e32 v37, v117
	v_mov_b32_e32 v38, v118
	v_mov_b32_e32 v39, v119
	v_cndmask_b32_e32 v5, v26, v5, vcc
	v_rsq_f32_e32 v5, v5
	v_lshl_add_u64 v[40:41], v[12:13], 0, v[16:17]
	v_mul_f32_e32 v16, 0x45800000, v5
	v_cndmask_b32_e32 v42, v5, v16, vcc
	v_pk_mul_f32 v[26:27], v[74:75], v[42:43] op_sel_hi:[1,0]
	v_pk_mul_f32 v[16:17], v[72:73], v[42:43] op_sel_hi:[1,0]
	v_pk_mul_f32 v[44:45], v[78:79], v[42:43] op_sel_hi:[1,0]
	v_pk_mul_f32 v[46:47], v[76:77], v[42:43] op_sel_hi:[1,0]
	v_cmp_lt_i32_e32 vcc, s5, v4
	v_pk_mul_f32 v[28:29], v[28:29], v[42:43] op_sel_hi:[1,0]
	v_pk_mul_f32 v[0:1], v[0:1], v[42:43] op_sel_hi:[1,0]
	s_or_b64 s[0:1], vcc, s[0:1]
	v_pk_mul_f32 v[30:31], v[30:31], v[42:43] op_sel_hi:[1,0]
	v_pk_fma_f32 v[16:17], v[22:23], v[16:17], v[18:19]
	v_pk_fma_f32 v[18:19], v[24:25], v[26:27], v[20:21]
	v_pk_fma_f32 v[20:21], v[32:33], v[46:47], v[36:37]
	v_pk_fma_f32 v[22:23], v[34:35], v[44:45], v[38:39]
	global_store_dwordx4 v[40:41], v[16:19], off nt
	global_store_dwordx4 v[40:41], v[20:23], off offset:16 nt
	s_nop 0
	v_mov_b32_e32 v16, v120
	v_mov_b32_e32 v17, v121
	v_mov_b32_e32 v18, v122
	v_mov_b32_e32 v19, v123
	s_nop 0
	v_mov_b32_e32 v20, v136
	v_mov_b32_e32 v21, v137
	v_mov_b32_e32 v22, v138
	v_mov_b32_e32 v23, v139
	v_mov_b32_e32 v24, v140
	v_mov_b32_e32 v25, v141
	v_mov_b32_e32 v26, v142
	v_mov_b32_e32 v27, v143
	v_mov_b32_e32 v32, v124
	v_mov_b32_e32 v33, v125
	v_mov_b32_e32 v34, v126
	v_mov_b32_e32 v35, v127
	v_pk_mul_f32 v[36:37], v[2:3], v[42:43] op_sel_hi:[1,0]
	v_pk_fma_f32 v[0:1], v[20:21], v[0:1], v[16:17]
	v_pk_fma_f32 v[2:3], v[22:23], v[28:29], v[18:19]
	v_pk_fma_f32 v[16:17], v[24:25], v[36:37], v[32:33]
	v_pk_fma_f32 v[18:19], v[26:27], v[30:31], v[34:35]
	global_store_dwordx4 v[40:41], v[0:3], off offset:2048 nt
	global_store_dwordx4 v[40:41], v[16:19], off offset:2064 nt
	s_andn2_b64 exec, exec, s[0:1]
	s_cbranch_execnz .LBB0_1619
